# phase 0 x->bf16 rows: dedicated loop with the next row's loads in flight (two register sets) and DPP row-sum reduction instead of ds_bpermute
# baseline (speedup 1.0000x reference)
; DI int tidx() { int t = __builtin_amdgcn_workitem_id_x(); asm volatile("" : "+v"(t)); return t; }
; DI unsigned pk2(float lo, float hi) { unsigned r; asm("v_cvt_pk_bf16_f32 %0, %1, %2" : "=v"(r) : "v"(lo), "v"(hi)); return r; }
; DI void xconv_item(const P& p, int it) {
;   const int lane = tidx() & 63, wave = __builtin_amdgcn_readfirstlane(tidx() >> 6);
;   const int row = it * 4 + wave;
;   const float* x = (row < NTP) ? (p.x_p + (size_t)row * DM) : (p.x_s + (size_t)(row - NTP) * DM);
;   bf16_t* xb = (bf16_t*)(p.ws + W_XB) + (size_t)row * DM;
;   float ss = 0.f;
; #pragma unroll
;   for (int j = 0; j < 4; ++j) {
;     const f32x4 v = *(const f32x4*)(x + j * 256 + lane * 4);
;     ss += v.x * v.x + v.y * v.y + v.z * v.z + v.w * v.w;
;     *(u32x2*)(xb + j * 256 + lane * 4) = u32x2{pk2(v.x, v.y), pk2(v.z, v.w)};
;   }
;   ss = wave_sum(ss);
;   if (lane < 16) ((float*)(p.ws + W_SS))[(size_t)row * 16 + lane] = (lane == 0) ? ss : 0.f;
; }
.LBB0_2047:
	v_and_b32_e32 v0, 63, v0
	v_lshlrev_b32_e32 v241, 4, v0
	v_readlane_b32 s20, v238, 31
	v_readlane_b32 s21, v238, 32
	global_load_dwordx4 v[104:107], v241, s[2:3]
	global_load_dwordx4 v[108:111], v241, s[2:3] offset:1024
	global_load_dwordx4 v[112:115], v241, s[2:3] offset:2048
	global_load_dwordx4 v[2:5], v241, s[2:3] offset:3072
	s_load_dword s20, s[20:21], 0x0
	v_lshlrev_b32_e32 v7, 3, v0
	s_waitcnt lgkmcnt(0)
	s_lshl_b32 s21, s20, 2
.Lxc_loop:
	s_add_i32 s22, s14, s20
	s_add_i32 s23, s0, s21
	s_cmpk_gt_i32 s22, 0x27df
	s_cbranch_scc1 .Lxc_last_a
	s_cmpk_gt_i32 s23, 0x7fff
	s_cbranch_scc1 .Lxc_sr_a
	s_lshl_b32 s2, s23, 12
	s_add_u32 s2, s16, s2
	s_addc_u32 s3, s17, 0
	s_branch .Lxc_pf_a
.Lxc_sr_a:
	s_add_i32 s2, s23, 0xffff8000
	s_lshl_b32 s2, s2, 12
	s_add_u32 s2, s18, s2
	s_addc_u32 s3, s19, 0
.Lxc_pf_a:
	global_load_dwordx4 v[116:119], v241, s[2:3]
	global_load_dwordx4 v[120:123], v241, s[2:3] offset:1024
	global_load_dwordx4 v[100:103], v241, s[2:3] offset:2048
	global_load_dwordx4 v[244:247], v241, s[2:3] offset:3072
	s_waitcnt vmcnt(4)
	s_lshl_b64 s[4:5], s[0:1], 11
	s_add_u32 s4, s74, s4
	s_addc_u32 s5, s75, s5
	v_mul_f32_e32 v8, v105, v105
	v_fmac_f32_e32 v8, v104, v104
	v_fmac_f32_e32 v8, v106, v106
	v_fmac_f32_e32 v8, v107, v107
	v_cvt_pk_bf16_f32 v104, v104, v105
	v_cvt_pk_bf16_f32 v105, v106, v107
	global_store_dwordx2 v7, v[104:105], s[4:5]
	v_mul_f32_e32 v9, v109, v109
	v_fmac_f32_e32 v9, v108, v108
	v_fmac_f32_e32 v9, v110, v110
	v_fmac_f32_e32 v9, v111, v111
	v_cvt_pk_bf16_f32 v108, v108, v109
	v_cvt_pk_bf16_f32 v109, v110, v111
	global_store_dwordx2 v7, v[108:109], s[4:5] offset:512
	v_add_f32_e32 v8, v8, v9
	v_mul_f32_e32 v9, v113, v113
	v_fmac_f32_e32 v9, v112, v112
	v_fmac_f32_e32 v9, v114, v114
	v_fmac_f32_e32 v9, v115, v115
	v_cvt_pk_bf16_f32 v112, v112, v113
	v_cvt_pk_bf16_f32 v113, v114, v115
	global_store_dwordx2 v7, v[112:113], s[4:5] offset:1024
	v_add_f32_e32 v8, v8, v9
	v_mul_f32_e32 v6, v3, v3
	v_fmac_f32_e32 v6, v2, v2
	v_fmac_f32_e32 v6, v4, v4
	v_fmac_f32_e32 v6, v5, v5
	v_cvt_pk_bf16_f32 v2, v2, v3
	v_cvt_pk_bf16_f32 v3, v4, v5
	global_store_dwordx2 v7, v[2:3], s[4:5] offset:1536
	v_add_f32_e32 v6, v8, v6
	s_nop 1
	v_add_f32_dpp v6, v6, v6 quad_perm:[1,0,3,2] row_mask:0xf bank_mask:0xf bound_ctrl:1
	s_nop 1
	v_add_f32_dpp v6, v6, v6 quad_perm:[2,3,0,1] row_mask:0xf bank_mask:0xf bound_ctrl:1
	s_nop 1
	v_add_f32_dpp v6, v6, v6 row_half_mirror row_mask:0xf bank_mask:0xf bound_ctrl:1
	s_nop 1
	v_add_f32_dpp v6, v6, v6 row_mirror row_mask:0xf bank_mask:0xf bound_ctrl:1
	s_nop 1
	v_readlane_b32 s2, v6, 0
	v_readlane_b32 s3, v6, 16
	v_readlane_b32 s4, v6, 32
	v_readlane_b32 s5, v6, 48
	s_nop 0
	v_mov_b32_e32 v242, s2
	v_add_f32_e32 v242, s3, v242
	v_add_f32_e32 v242, s4, v242
	v_add_f32_e32 v242, s5, v242
	v_cmp_gt_u32_e32 vcc, 16, v0
	s_and_saveexec_b64 s[2:3], vcc
	s_cbranch_execz .Lxc_ssd_a
	s_lshl_b64 s[0:1], s[0:1], 6
	v_cmp_eq_u32_e32 vcc, 0, v0
	s_add_u32 s0, s66, s0
	s_addc_u32 s1, s67, s1
	v_cndmask_b32_e32 v242, 0, v242, vcc
	v_lshlrev_b32_e32 v9, 2, v0
	global_store_dword v9, v242, s[0:1]
.Lxc_ssd_a:
	s_or_b64 exec, exec, s[2:3]
	s_mov_b32 s14, s22
	s_mov_b32 s0, s23
	s_mov_b32 s1, 0
	s_add_i32 s22, s14, s20
	s_add_i32 s23, s0, s21
	s_cmpk_gt_i32 s22, 0x27df
	s_cbranch_scc1 .Lxc_last_b
	s_cmpk_gt_i32 s23, 0x7fff
	s_cbranch_scc1 .Lxc_sr_b
	s_lshl_b32 s2, s23, 12
	s_add_u32 s2, s16, s2
	s_addc_u32 s3, s17, 0
	s_branch .Lxc_pf_b

; DI int tidx() { int t = __builtin_amdgcn_workitem_id_x(); asm volatile("" : "+v"(t)); return t; }
; DI unsigned pk2(float lo, float hi) { unsigned r; asm("v_cvt_pk_bf16_f32 %0, %1, %2" : "=v"(r) : "v"(lo), "v"(hi)); return r; }
; DI void xconv_item(const P& p, int it) {
;   const int lane = tidx() & 63, wave = __builtin_amdgcn_readfirstlane(tidx() >> 6);
;   const int row = it * 4 + wave;
;   const float* x = (row < NTP) ? (p.x_p + (size_t)row * DM) : (p.x_s + (size_t)(row - NTP) * DM);
;   bf16_t* xb = (bf16_t*)(p.ws + W_XB) + (size_t)row * DM;
;   float ss = 0.f;
; #pragma unroll
;   for (int j = 0; j < 4; ++j) {
;     const f32x4 v = *(const f32x4*)(x + j * 256 + lane * 4);
;     ss += v.x * v.x + v.y * v.y + v.z * v.z + v.w * v.w;
;     *(u32x2*)(xb + j * 256 + lane * 4) = u32x2{pk2(v.x, v.y), pk2(v.z, v.w)};
;   }
;   ss = wave_sum(ss);
;   if (lane < 16) ((float*)(p.ws + W_SS))[(size_t)row * 16 + lane] = (lane == 0) ? ss : 0.f;
; }
.Lxc_pf_b:
	global_load_dwordx4 v[104:107], v241, s[2:3]
	global_load_dwordx4 v[108:111], v241, s[2:3] offset:1024
	global_load_dwordx4 v[112:115], v241, s[2:3] offset:2048
	global_load_dwordx4 v[2:5], v241, s[2:3] offset:3072
	s_waitcnt vmcnt(4)
	s_lshl_b64 s[4:5], s[0:1], 11
	s_add_u32 s4, s74, s4
	s_addc_u32 s5, s75, s5
	v_mul_f32_e32 v8, v117, v117
	v_fmac_f32_e32 v8, v116, v116
	v_fmac_f32_e32 v8, v118, v118
	v_fmac_f32_e32 v8, v119, v119
	v_cvt_pk_bf16_f32 v116, v116, v117
	v_cvt_pk_bf16_f32 v117, v118, v119
	global_store_dwordx2 v7, v[116:117], s[4:5]
	v_mul_f32_e32 v9, v121, v121
	v_fmac_f32_e32 v9, v120, v120
	v_fmac_f32_e32 v9, v122, v122
	v_fmac_f32_e32 v9, v123, v123
	v_cvt_pk_bf16_f32 v120, v120, v121
	v_cvt_pk_bf16_f32 v121, v122, v123
	global_store_dwordx2 v7, v[120:121], s[4:5] offset:512
	v_add_f32_e32 v8, v8, v9
	v_mul_f32_e32 v9, v101, v101
	v_fmac_f32_e32 v9, v100, v100
	v_fmac_f32_e32 v9, v102, v102
	v_fmac_f32_e32 v9, v103, v103
	v_cvt_pk_bf16_f32 v100, v100, v101
	v_cvt_pk_bf16_f32 v101, v102, v103
	global_store_dwordx2 v7, v[100:101], s[4:5] offset:1024
	v_add_f32_e32 v8, v8, v9
	v_mul_f32_e32 v6, v245, v245
	v_fmac_f32_e32 v6, v244, v244
	v_fmac_f32_e32 v6, v246, v246
	v_fmac_f32_e32 v6, v247, v247
	v_cvt_pk_bf16_f32 v244, v244, v245
	v_cvt_pk_bf16_f32 v245, v246, v247
	global_store_dwordx2 v7, v[244:245], s[4:5] offset:1536
	v_add_f32_e32 v6, v8, v6
	s_nop 1
	v_add_f32_dpp v6, v6, v6 quad_perm:[1,0,3,2] row_mask:0xf bank_mask:0xf bound_ctrl:1
	s_nop 1
	v_add_f32_dpp v6, v6, v6 quad_perm:[2,3,0,1] row_mask:0xf bank_mask:0xf bound_ctrl:1
	s_nop 1
	v_add_f32_dpp v6, v6, v6 row_half_mirror row_mask:0xf bank_mask:0xf bound_ctrl:1
	s_nop 1
	v_add_f32_dpp v6, v6, v6 row_mirror row_mask:0xf bank_mask:0xf bound_ctrl:1
	s_nop 1
	v_readlane_b32 s2, v6, 0
	v_readlane_b32 s3, v6, 16
	v_readlane_b32 s4, v6, 32
	v_readlane_b32 s5, v6, 48
	s_nop 0
	v_mov_b32_e32 v242, s2
	v_add_f32_e32 v242, s3, v242
	v_add_f32_e32 v242, s4, v242
	v_add_f32_e32 v242, s5, v242
	v_cmp_gt_u32_e32 vcc, 16, v0
	s_and_saveexec_b64 s[2:3], vcc
	s_cbranch_execz .Lxc_ssd_b
	s_lshl_b64 s[0:1], s[0:1], 6
	v_cmp_eq_u32_e32 vcc, 0, v0
	s_add_u32 s0, s66, s0
	s_addc_u32 s1, s67, s1
	v_cndmask_b32_e32 v242, 0, v242, vcc
	v_lshlrev_b32_e32 v9, 2, v0
	global_store_dword v9, v242, s[0:1]
.Lxc_ssd_b:
	s_or_b64 exec, exec, s[2:3]
	s_mov_b32 s14, s22
	s_mov_b32 s0, s23
	s_mov_b32 s1, 0
	s_branch .Lxc_loop
.Lxc_last_a:
	s_waitcnt vmcnt(0)
	s_lshl_b64 s[4:5], s[0:1], 11
	s_add_u32 s4, s74, s4
	s_addc_u32 s5, s75, s5
	v_mul_f32_e32 v8, v105, v105
	v_fmac_f32_e32 v8, v104, v104
	v_fmac_f32_e32 v8, v106, v106
	v_fmac_f32_e32 v8, v107, v107
	v_cvt_pk_bf16_f32 v104, v104, v105
	v_cvt_pk_bf16_f32 v105, v106, v107
	global_store_dwordx2 v7, v[104:105], s[4:5]
	v_mul_f32_e32 v9, v109, v109
	v_fmac_f32_e32 v9, v108, v108
	v_fmac_f32_e32 v9, v110, v110
	v_fmac_f32_e32 v9, v111, v111
	v_cvt_pk_bf16_f32 v108, v108, v109
	v_cvt_pk_bf16_f32 v109, v110, v111
	global_store_dwordx2 v7, v[108:109], s[4:5] offset:512
	v_add_f32_e32 v8, v8, v9
	v_mul_f32_e32 v9, v113, v113
	v_fmac_f32_e32 v9, v112, v112
	v_fmac_f32_e32 v9, v114, v114
	v_fmac_f32_e32 v9, v115, v115
	v_cvt_pk_bf16_f32 v112, v112, v113
	v_cvt_pk_bf16_f32 v113, v114, v115
	global_store_dwordx2 v7, v[112:113], s[4:5] offset:1024
	v_add_f32_e32 v8, v8, v9
	v_mul_f32_e32 v6, v3, v3
	v_fmac_f32_e32 v6, v2, v2
	v_fmac_f32_e32 v6, v4, v4
	v_fmac_f32_e32 v6, v5, v5
	v_cvt_pk_bf16_f32 v2, v2, v3
	v_cvt_pk_bf16_f32 v3, v4, v5
	global_store_dwordx2 v7, v[2:3], s[4:5] offset:1536
	v_add_f32_e32 v6, v8, v6
	s_nop 1
	v_add_f32_dpp v6, v6, v6 quad_perm:[1,0,3,2] row_mask:0xf bank_mask:0xf bound_ctrl:1
	s_nop 1
	v_add_f32_dpp v6, v6, v6 quad_perm:[2,3,0,1] row_mask:0xf bank_mask:0xf bound_ctrl:1
	s_nop 1
	v_add_f32_dpp v6, v6, v6 row_half_mirror row_mask:0xf bank_mask:0xf bound_ctrl:1
	s_nop 1
	v_add_f32_dpp v6, v6, v6 row_mirror row_mask:0xf bank_mask:0xf bound_ctrl:1
	s_nop 1
	v_readlane_b32 s2, v6, 0
	v_readlane_b32 s3, v6, 16
	v_readlane_b32 s4, v6, 32
	v_readlane_b32 s5, v6, 48
	s_nop 0
	v_mov_b32_e32 v242, s2
	v_add_f32_e32 v242, s3, v242
	v_add_f32_e32 v242, s4, v242
	v_add_f32_e32 v242, s5, v242
	v_cmp_gt_u32_e32 vcc, 16, v0
	s_and_saveexec_b64 s[2:3], vcc
	s_cbranch_execz .Lxc_ssd_la
	s_lshl_b64 s[0:1], s[0:1], 6
	v_cmp_eq_u32_e32 vcc, 0, v0
	s_add_u32 s0, s66, s0
	s_addc_u32 s1, s67, s1
	v_cndmask_b32_e32 v242, 0, v242, vcc
	v_lshlrev_b32_e32 v9, 2, v0
	global_store_dword v9, v242, s[0:1]

; DI int tidx() { int t = __builtin_amdgcn_workitem_id_x(); asm volatile("" : "+v"(t)); return t; }
; DI unsigned pk2(float lo, float hi) { unsigned r; asm("v_cvt_pk_bf16_f32 %0, %1, %2" : "=v"(r) : "v"(lo), "v"(hi)); return r; }
; DI void xconv_item(const P& p, int it) {
;   const int lane = tidx() & 63, wave = __builtin_amdgcn_readfirstlane(tidx() >> 6);
;   const int row = it * 4 + wave;
;   const float* x = (row < NTP) ? (p.x_p + (size_t)row * DM) : (p.x_s + (size_t)(row - NTP) * DM);
;   bf16_t* xb = (bf16_t*)(p.ws + W_XB) + (size_t)row * DM;
;   float ss = 0.f;
; #pragma unroll
;   for (int j = 0; j < 4; ++j) {
;     const f32x4 v = *(const f32x4*)(x + j * 256 + lane * 4);
;     ss += v.x * v.x + v.y * v.y + v.z * v.z + v.w * v.w;
;     *(u32x2*)(xb + j * 256 + lane * 4) = u32x2{pk2(v.x, v.y), pk2(v.z, v.w)};
;   }
;   ss = wave_sum(ss);
;   if (lane < 16) ((float*)(p.ws + W_SS))[(size_t)row * 16 + lane] = (lane == 0) ? ss : 0.f;
; }
.Lxc_last_b:
	s_waitcnt vmcnt(0)
	s_lshl_b64 s[4:5], s[0:1], 11
	s_add_u32 s4, s74, s4
	s_addc_u32 s5, s75, s5
	v_mul_f32_e32 v8, v117, v117
	v_fmac_f32_e32 v8, v116, v116
	v_fmac_f32_e32 v8, v118, v118
	v_fmac_f32_e32 v8, v119, v119
	v_cvt_pk_bf16_f32 v116, v116, v117
	v_cvt_pk_bf16_f32 v117, v118, v119
	global_store_dwordx2 v7, v[116:117], s[4:5]
	v_mul_f32_e32 v9, v121, v121
	v_fmac_f32_e32 v9, v120, v120
	v_fmac_f32_e32 v9, v122, v122
	v_fmac_f32_e32 v9, v123, v123
	v_cvt_pk_bf16_f32 v120, v120, v121
	v_cvt_pk_bf16_f32 v121, v122, v123
	global_store_dwordx2 v7, v[120:121], s[4:5] offset:512
	v_add_f32_e32 v8, v8, v9
	v_mul_f32_e32 v9, v101, v101
	v_fmac_f32_e32 v9, v100, v100
	v_fmac_f32_e32 v9, v102, v102
	v_fmac_f32_e32 v9, v103, v103
	v_cvt_pk_bf16_f32 v100, v100, v101
	v_cvt_pk_bf16_f32 v101, v102, v103
	global_store_dwordx2 v7, v[100:101], s[4:5] offset:1024
	v_add_f32_e32 v8, v8, v9
	v_mul_f32_e32 v6, v245, v245
	v_fmac_f32_e32 v6, v244, v244
	v_fmac_f32_e32 v6, v246, v246
	v_fmac_f32_e32 v6, v247, v247
	v_cvt_pk_bf16_f32 v244, v244, v245
	v_cvt_pk_bf16_f32 v245, v246, v247
	global_store_dwordx2 v7, v[244:245], s[4:5] offset:1536
	v_add_f32_e32 v6, v8, v6
	s_nop 1
	v_add_f32_dpp v6, v6, v6 quad_perm:[1,0,3,2] row_mask:0xf bank_mask:0xf bound_ctrl:1
	s_nop 1
	v_add_f32_dpp v6, v6, v6 quad_perm:[2,3,0,1] row_mask:0xf bank_mask:0xf bound_ctrl:1
	s_nop 1
	v_add_f32_dpp v6, v6, v6 row_half_mirror row_mask:0xf bank_mask:0xf bound_ctrl:1
	s_nop 1
	v_add_f32_dpp v6, v6, v6 row_mirror row_mask:0xf bank_mask:0xf bound_ctrl:1
	s_nop 1
	v_readlane_b32 s2, v6, 0
	v_readlane_b32 s3, v6, 16
	v_readlane_b32 s4, v6, 32
	v_readlane_b32 s5, v6, 48
	s_nop 0
	v_mov_b32_e32 v242, s2
	v_add_f32_e32 v242, s3, v242
	v_add_f32_e32 v242, s4, v242
	v_add_f32_e32 v242, s5, v242
	v_cmp_gt_u32_e32 vcc, 16, v0
	s_and_saveexec_b64 s[2:3], vcc
	s_cbranch_execz .Lxc_ssd_lb
	s_lshl_b64 s[0:1], s[0:1], 6
	v_cmp_eq_u32_e32 vcc, 0, v0
	s_add_u32 s0, s66, s0
	s_addc_u32 s1, s67, s1
	v_cndmask_b32_e32 v242, 0, v242, vcc
	v_lshlrev_b32_e32 v9, 2, v0
	global_store_dword v9, v242, s[0:1]

; PHASE_FN void phase0(const P& p, char* lds) {
;     ...
;   for (int it = blockIdx.x; it < R9; it += gridDim.x) {
;     if (it < R4) weight_item(p, 0, it, tile);
;     else if (it < R5) xconv_item(p, it - R4);
;     else if (it < R6) rope_item(p, it - R5);
;     else conv_cache_ki(p, it - R6);
;   }
.Lxc_exit:
	v_readlane_b32 s20, v240, 10
	v_readlane_b32 s21, v240, 11
	v_readlane_b32 s22, v240, 12
	v_readlane_b32 s23, v240, 13
	s_mov_b64 s[2:3], exec
